# P12 wide row pass: f loads (written by the previous phase) without the non-temporal hint
# speedup vs baseline: 1.0076x; 1.0076x over previous
; __device__ __forceinline__ f32x4 up4(u32x2 w) { return (f32x4){bf_lo(w.x), bf_hi(w.x), bf_lo(w.y), bf_hi(w.y)}; }
; __device__ __forceinline__ void row_pass1(const Args& a, int row_lo, int row_hi, int gw, int NGW, int lane) {
;     ...
;         for (int r = 0; r < 2; ++r) { const int row = r0 + r; if (row >= row_hi) break;
;             const float rstd = rsqrtf(rs[r] * (1.f / DM) + EPS); f32x4 v[4]; float s = 0.f;
; #pragma unroll
;             for (int j = 0; j < 4; ++j) { v[j] = xv[r][j] + up4(yv[r][j]) * rstd * gp[j]; s += (v[j][0] * v[j][0] + v[j][1] * v[j][1]) + (v[j][2] * v[j][2] + v[j][3] * v[j][3]); }
; template <bool DRYR = false>
; __device__ __forceinline__ void row_pass2(const Args& a, int row_lo, int row_hi, int gw, int NGW, int lane) {
;     ...
;     for (int r0 = row_lo + 2 * gw; r0 < row_hi; r0 += 2 * NGW) {
;         f32x4 xv[2][4]; u32x2 fv[2][4]; float rs[2];
; #pragma unroll
;         for (int r = 0; r < 2; ++r) { const int row = (r0 + r < row_hi) ? r0 + r : r0; rs[r] = rss[row];
;             const f32x4* xo = (const f32x4*)(XO + (size_t)row * DM) + lane; const u32x2* fr = (const u32x2*)(F + (size_t)row * DM) + lane;
; #pragma unroll
;             for (int j = 0; j < 4; ++j) { xv[r][j] = xo[64 * j]; fv[r][j] = fr[64 * j]; } }
; #pragma unroll
;         for (int r = 0; r < 2; ++r) { const int row = r0 + r; if (row >= row_hi) break;
;             const float rstd = rsqrtf(rs[r] * (1.f / DM) + EPS); f32x4* xo = (f32x4*)(XO + (size_t)row * DM) + lane;
; #pragma unroll
;             for (int j = 0; j < 4; ++j) { const f32x4 o = xv[r][j] + up4(fv[r][j]) * rstd * gp[j]; if (!DRYR || o[0] == 123.456f) xo[64 * j] = o; } }
.Lxo_loop:
	global_load_dwordx2 v[80:81], v145, s[16:17]
	global_load_dwordx2 v[82:83], v145, s[18:19]
	global_load_dwordx4 v[48:51], v144, s[24:25] nt
	global_load_dwordx4 v[52:55], v144, s[24:25] offset:1024 nt
	global_load_dwordx4 v[16:19], v148, s[20:21] nt
	global_load_dwordx4 v[20:23], v148, s[20:21] offset:16 nt
	global_load_dwordx4 v[24:27], v148, s[20:21] offset:2048 nt
	global_load_dwordx4 v[28:31], v148, s[20:21] offset:2064 nt
	global_load_dwordx4 v[64:67], v144, s[26:27]
	global_load_dwordx4 v[68:71], v144, s[26:27] offset:1024
	global_load_dwordx4 v[56:59], v144, s[24:25] offset:2048 nt
	global_load_dwordx4 v[60:63], v144, s[24:25] offset:3072 nt
	global_load_dwordx4 v[32:35], v149, s[20:21] nt
	global_load_dwordx4 v[36:39], v149, s[20:21] offset:16 nt
	global_load_dwordx4 v[40:43], v149, s[20:21] offset:2048 nt
	global_load_dwordx4 v[44:47], v149, s[20:21] offset:2064 nt
	global_load_dwordx4 v[72:75], v144, s[26:27] offset:2048
	global_load_dwordx4 v[76:79], v144, s[26:27] offset:3072
	s_waitcnt vmcnt(8)
	v_fmamk_f32 v104, v80, 0x3a800000, v116
	v_mul_f32_e32 v105, 0x4b800000, v104
	v_cmp_gt_f32_e32 vcc, s3, v104
	s_nop 1
	v_cndmask_b32_e32 v104, v104, v105, vcc
	v_rsq_f32_e32 v104, v104
	s_nop 0
	v_mul_f32_e32 v105, 0x45800000, v104
	v_cndmask_b32_e32 v104, v104, v105, vcc
	v_fmamk_f32 v106, v82, 0x3a800000, v116
	v_mul_f32_e32 v107, 0x4b800000, v106
	v_cmp_gt_f32_e32 vcc, s3, v106
	s_nop 1
	v_cndmask_b32_e32 v106, v106, v107, vcc
	v_rsq_f32_e32 v106, v106
	s_nop 0
	v_mul_f32_e32 v107, 0x45800000, v106
	v_cndmask_b32_e32 v106, v106, v107, vcc
	v_lshlrev_b32_e32 v120, 16, v48
	v_and_b32_e32 v121, 0xffff0000, v48
	v_lshlrev_b32_e32 v122, 16, v49
	v_and_b32_e32 v123, 0xffff0000, v49
	v_lshlrev_b32_e32 v150, 16, v64
	v_and_b32_e32 v151, 0xffff0000, v64
	v_lshlrev_b32_e32 v152, 16, v65
	v_and_b32_e32 v153, 0xffff0000, v65
	v_pk_mul_f32 v[120:121], v[104:105], v[120:121] op_sel_hi:[0,1]
	v_pk_mul_f32 v[122:123], v[104:105], v[122:123] op_sel_hi:[0,1]
	v_pk_mul_f32 v[150:151], v[106:107], v[150:151] op_sel_hi:[0,1]
	v_pk_mul_f32 v[152:153], v[106:107], v[152:153] op_sel_hi:[0,1]
	v_pk_fma_f32 v[16:17], v[84:85], v[120:121], v[16:17]
	v_pk_fma_f32 v[18:19], v[86:87], v[122:123], v[18:19]
	v_pk_fma_f32 v[16:17], v[0:1], v[150:151], v[16:17]
	v_pk_fma_f32 v[18:19], v[2:3], v[152:153], v[18:19]
	v_lshlrev_b32_e32 v124, 16, v50
	v_and_b32_e32 v125, 0xffff0000, v50
	v_lshlrev_b32_e32 v126, 16, v51
	v_and_b32_e32 v127, 0xffff0000, v51
	v_lshlrev_b32_e32 v154, 16, v66
	v_and_b32_e32 v155, 0xffff0000, v66
	v_lshlrev_b32_e32 v156, 16, v67
	v_and_b32_e32 v157, 0xffff0000, v67
	v_pk_mul_f32 v[124:125], v[104:105], v[124:125] op_sel_hi:[0,1]
	v_pk_mul_f32 v[126:127], v[104:105], v[126:127] op_sel_hi:[0,1]
	v_pk_mul_f32 v[154:155], v[106:107], v[154:155] op_sel_hi:[0,1]
	v_pk_mul_f32 v[156:157], v[106:107], v[156:157] op_sel_hi:[0,1]
	v_pk_fma_f32 v[20:21], v[88:89], v[124:125], v[20:21]
	v_pk_fma_f32 v[22:23], v[90:91], v[126:127], v[22:23]
	v_pk_fma_f32 v[20:21], v[4:5], v[154:155], v[20:21]
	v_pk_fma_f32 v[22:23], v[6:7], v[156:157], v[22:23]
	v_lshlrev_b32_e32 v128, 16, v52
	v_and_b32_e32 v129, 0xffff0000, v52
	v_lshlrev_b32_e32 v130, 16, v53
	v_and_b32_e32 v131, 0xffff0000, v53
	v_lshlrev_b32_e32 v158, 16, v68
	v_and_b32_e32 v159, 0xffff0000, v68
	v_lshlrev_b32_e32 v160, 16, v69
	v_and_b32_e32 v161, 0xffff0000, v69
	v_pk_mul_f32 v[128:129], v[104:105], v[128:129] op_sel_hi:[0,1]
	v_pk_mul_f32 v[130:131], v[104:105], v[130:131] op_sel_hi:[0,1]
	v_pk_mul_f32 v[158:159], v[106:107], v[158:159] op_sel_hi:[0,1]
	v_pk_mul_f32 v[160:161], v[106:107], v[160:161] op_sel_hi:[0,1]
	v_pk_fma_f32 v[24:25], v[92:93], v[128:129], v[24:25]
	v_pk_fma_f32 v[26:27], v[94:95], v[130:131], v[26:27]
	v_pk_fma_f32 v[24:25], v[8:9], v[158:159], v[24:25]
	v_pk_fma_f32 v[26:27], v[10:11], v[160:161], v[26:27]
	v_lshlrev_b32_e32 v132, 16, v54
	v_and_b32_e32 v133, 0xffff0000, v54
	v_lshlrev_b32_e32 v134, 16, v55
	v_and_b32_e32 v135, 0xffff0000, v55
	v_lshlrev_b32_e32 v162, 16, v70
	v_and_b32_e32 v163, 0xffff0000, v70
	v_lshlrev_b32_e32 v164, 16, v71
	v_and_b32_e32 v165, 0xffff0000, v71
	v_pk_mul_f32 v[132:133], v[104:105], v[132:133] op_sel_hi:[0,1]
	v_pk_mul_f32 v[134:135], v[104:105], v[134:135] op_sel_hi:[0,1]
	v_pk_mul_f32 v[162:163], v[106:107], v[162:163] op_sel_hi:[0,1]
	v_pk_mul_f32 v[164:165], v[106:107], v[164:165] op_sel_hi:[0,1]
	v_pk_fma_f32 v[28:29], v[96:97], v[132:133], v[28:29]
	v_pk_fma_f32 v[30:31], v[98:99], v[134:135], v[30:31]
	v_pk_fma_f32 v[28:29], v[12:13], v[162:163], v[28:29]
	v_pk_fma_f32 v[30:31], v[14:15], v[164:165], v[30:31]
	global_store_dwordx4 v148, v[16:19], s[22:23] nt
	global_store_dwordx4 v148, v[20:23], s[22:23] offset:16 nt
	global_store_dwordx4 v148, v[24:27], s[22:23] offset:2048 nt
	global_store_dwordx4 v148, v[28:31], s[22:23] offset:2064 nt
	s_waitcnt vmcnt(4)
; __device__ __forceinline__ f32x4 up4(u32x2 w) { return (f32x4){bf_lo(w.x), bf_hi(w.x), bf_lo(w.y), bf_hi(w.y)}; }
; __device__ __forceinline__ void row_pass1(const Args& a, int row_lo, int row_hi, int gw, int NGW, int lane) {
;     ...
;         for (int r = 0; r < 2; ++r) { const int row = r0 + r; if (row >= row_hi) break;
;             const float rstd = rsqrtf(rs[r] * (1.f / DM) + EPS); f32x4 v[4]; float s = 0.f;
; #pragma unroll
;             for (int j = 0; j < 4; ++j) { v[j] = xv[r][j] + up4(yv[r][j]) * rstd * gp[j]; s += (v[j][0] * v[j][0] + v[j][1] * v[j][1]) + (v[j][2] * v[j][2] + v[j][3] * v[j][3]); }
; template <bool DRYR = false>
; __device__ __forceinline__ void row_pass2(const Args& a, int row_lo, int row_hi, int gw, int NGW, int lane) {
;     ...
;     for (int r0 = row_lo + 2 * gw; r0 < row_hi; r0 += 2 * NGW) {
;         f32x4 xv[2][4]; u32x2 fv[2][4]; float rs[2];
; #pragma unroll
;         for (int r = 0; r < 2; ++r) { const int row = (r0 + r < row_hi) ? r0 + r : r0; rs[r] = rss[row];
;             const f32x4* xo = (const f32x4*)(XO + (size_t)row * DM) + lane; const u32x2* fr = (const u32x2*)(F + (size_t)row * DM) + lane;
; #pragma unroll
;             for (int j = 0; j < 4; ++j) { xv[r][j] = xo[64 * j]; fv[r][j] = fr[64 * j]; } }
; #pragma unroll
;         for (int r = 0; r < 2; ++r) { const int row = r0 + r; if (row >= row_hi) break;
;             const float rstd = rsqrtf(rs[r] * (1.f / DM) + EPS); f32x4* xo = (f32x4*)(XO + (size_t)row * DM) + lane;
; #pragma unroll
;             for (int j = 0; j < 4; ++j) { const f32x4 o = xv[r][j] + up4(fv[r][j]) * rstd * gp[j]; if (!DRYR || o[0] == 123.456f) xo[64 * j] = o; } }
	v_fmamk_f32 v104, v81, 0x3a800000, v116
	v_mul_f32_e32 v105, 0x4b800000, v104
	v_cmp_gt_f32_e32 vcc, s3, v104
	s_nop 1
	v_cndmask_b32_e32 v104, v104, v105, vcc
	v_rsq_f32_e32 v104, v104
	s_nop 0
	v_mul_f32_e32 v105, 0x45800000, v104
	v_cndmask_b32_e32 v104, v104, v105, vcc
	v_fmamk_f32 v106, v83, 0x3a800000, v116
	v_mul_f32_e32 v107, 0x4b800000, v106
	v_cmp_gt_f32_e32 vcc, s3, v106
	s_nop 1
	v_cndmask_b32_e32 v106, v106, v107, vcc
	v_rsq_f32_e32 v106, v106
	s_nop 0
	v_mul_f32_e32 v107, 0x45800000, v106
	v_cndmask_b32_e32 v106, v106, v107, vcc
	v_lshlrev_b32_e32 v120, 16, v56
	v_and_b32_e32 v121, 0xffff0000, v56
	v_lshlrev_b32_e32 v122, 16, v57
	v_and_b32_e32 v123, 0xffff0000, v57
	v_lshlrev_b32_e32 v150, 16, v72
	v_and_b32_e32 v151, 0xffff0000, v72
	v_lshlrev_b32_e32 v152, 16, v73
	v_and_b32_e32 v153, 0xffff0000, v73
	v_pk_mul_f32 v[120:121], v[104:105], v[120:121] op_sel_hi:[0,1]
	v_pk_mul_f32 v[122:123], v[104:105], v[122:123] op_sel_hi:[0,1]
	v_pk_mul_f32 v[150:151], v[106:107], v[150:151] op_sel_hi:[0,1]
	v_pk_mul_f32 v[152:153], v[106:107], v[152:153] op_sel_hi:[0,1]
	v_pk_fma_f32 v[32:33], v[84:85], v[120:121], v[32:33]
	v_pk_fma_f32 v[34:35], v[86:87], v[122:123], v[34:35]
	v_pk_fma_f32 v[32:33], v[0:1], v[150:151], v[32:33]
	v_pk_fma_f32 v[34:35], v[2:3], v[152:153], v[34:35]
	v_lshlrev_b32_e32 v124, 16, v58
	v_and_b32_e32 v125, 0xffff0000, v58
	v_lshlrev_b32_e32 v126, 16, v59
	v_and_b32_e32 v127, 0xffff0000, v59
	v_lshlrev_b32_e32 v154, 16, v74
	v_and_b32_e32 v155, 0xffff0000, v74
	v_lshlrev_b32_e32 v156, 16, v75
	v_and_b32_e32 v157, 0xffff0000, v75
	v_pk_mul_f32 v[124:125], v[104:105], v[124:125] op_sel_hi:[0,1]
	v_pk_mul_f32 v[126:127], v[104:105], v[126:127] op_sel_hi:[0,1]
	v_pk_mul_f32 v[154:155], v[106:107], v[154:155] op_sel_hi:[0,1]
	v_pk_mul_f32 v[156:157], v[106:107], v[156:157] op_sel_hi:[0,1]
	v_pk_fma_f32 v[36:37], v[88:89], v[124:125], v[36:37]
	v_pk_fma_f32 v[38:39], v[90:91], v[126:127], v[38:39]
	v_pk_fma_f32 v[36:37], v[4:5], v[154:155], v[36:37]
	v_pk_fma_f32 v[38:39], v[6:7], v[156:157], v[38:39]
	v_lshlrev_b32_e32 v128, 16, v60
	v_and_b32_e32 v129, 0xffff0000, v60
	v_lshlrev_b32_e32 v130, 16, v61
	v_and_b32_e32 v131, 0xffff0000, v61
	v_lshlrev_b32_e32 v158, 16, v76
	v_and_b32_e32 v159, 0xffff0000, v76
	v_lshlrev_b32_e32 v160, 16, v77
	v_and_b32_e32 v161, 0xffff0000, v77
	v_pk_mul_f32 v[128:129], v[104:105], v[128:129] op_sel_hi:[0,1]
	v_pk_mul_f32 v[130:131], v[104:105], v[130:131] op_sel_hi:[0,1]
	v_pk_mul_f32 v[158:159], v[106:107], v[158:159] op_sel_hi:[0,1]
	v_pk_mul_f32 v[160:161], v[106:107], v[160:161] op_sel_hi:[0,1]
	v_pk_fma_f32 v[40:41], v[92:93], v[128:129], v[40:41]
	v_pk_fma_f32 v[42:43], v[94:95], v[130:131], v[42:43]
	v_pk_fma_f32 v[40:41], v[8:9], v[158:159], v[40:41]
	v_pk_fma_f32 v[42:43], v[10:11], v[160:161], v[42:43]
	v_lshlrev_b32_e32 v132, 16, v62
	v_and_b32_e32 v133, 0xffff0000, v62
	v_lshlrev_b32_e32 v134, 16, v63
	v_and_b32_e32 v135, 0xffff0000, v63
	v_lshlrev_b32_e32 v162, 16, v78
	v_and_b32_e32 v163, 0xffff0000, v78
	v_lshlrev_b32_e32 v164, 16, v79
	v_and_b32_e32 v165, 0xffff0000, v79
	v_pk_mul_f32 v[132:133], v[104:105], v[132:133] op_sel_hi:[0,1]
	v_pk_mul_f32 v[134:135], v[104:105], v[134:135] op_sel_hi:[0,1]
	v_pk_mul_f32 v[162:163], v[106:107], v[162:163] op_sel_hi:[0,1]
	v_pk_mul_f32 v[164:165], v[106:107], v[164:165] op_sel_hi:[0,1]
	v_pk_fma_f32 v[44:45], v[96:97], v[132:133], v[44:45]
	v_pk_fma_f32 v[46:47], v[98:99], v[134:135], v[46:47]
	v_pk_fma_f32 v[44:45], v[12:13], v[162:163], v[44:45]
	v_pk_fma_f32 v[46:47], v[14:15], v[164:165], v[46:47]
	global_store_dwordx4 v149, v[32:35], s[22:23] nt
	global_store_dwordx4 v149, v[36:39], s[22:23] offset:16 nt
	global_store_dwordx4 v149, v[40:43], s[22:23] offset:2048 nt
	global_store_dwordx4 v149, v[44:47], s[22:23] offset:2064 nt
	s_add_i32 s0, s0, s4
	s_add_u32 s20, s20, s98
	s_addc_u32 s21, s21, 0
	s_add_u32 s22, s22, s98
	s_addc_u32 s23, s23, 0
	s_add_u32 s24, s24, s99
	s_addc_u32 s25, s25, 0
	s_add_u32 s26, s26, s99
	s_addc_u32 s27, s27, 0
	s_add_u32 s16, s16, s100
	s_addc_u32 s17, s17, 0
	s_add_u32 s18, s18, s100
	s_addc_u32 s19, s19, 0
	s_cmpk_gt_i32 s0, 0x3fff
	s_cbranch_scc0 .Lxo_loop
